# v39 plus phase-0 gain loads issued together behind a vmcnt(31) guard (never more than 63 loads outstanding)
# speedup vs baseline: 1.0035x; 1.0035x over previous
.LBB0_580:
	s_andn2_b64 vcc, exec, s[2:3]
	s_cbranch_vccnz .LBB0_647
	s_mov_b32 s2, 24
	s_ashr_i32 s3, s2, 31
	s_lshl_b64 s[2:3], s[2:3], 3
	s_add_u32 s2, s0, s2
	s_addc_u32 s3, s1, s3
	s_load_dwordx2 s[38:39], s[2:3], 0x0
	s_mov_b32 s2, 25
	s_ashr_i32 s3, s2, 31
	s_lshl_b64 s[2:3], s[2:3], 3
	s_add_u32 s2, s0, s2
	s_addc_u32 s3, s1, s3
	s_load_dwordx2 s[42:43], s[2:3], 0x0
	s_mov_b32 s2, 23
	s_ashr_i32 s3, s2, 31
	s_lshl_b64 s[2:3], s[2:3], 3
	s_add_u32 s2, s0, s2
	s_addc_u32 s3, s1, s3
	s_load_dwordx2 s[2:3], s[2:3], 0x0
	s_lshl_b32 s6, s4, 10
	s_ashr_i32 s7, s6, 31
	s_lshl_b64 s[6:7], s[6:7], 2
	s_waitcnt lgkmcnt(0)
	s_add_u32 s6, s2, s6
	s_addc_u32 s7, s3, s7
	s_add_i32 s10, s41, 0xe600
	s_and_b32 s11, s10, 0xffff
	s_mul_i32 s11, s11, 0xba2f
	s_lshr_b32 s20, s11, 23
	s_mul_i32 s11, s20, 0xb0
	s_sub_i32 s21, s10, s11
	s_and_b32 s44, s21, 0xffff
	s_lshl_b32 s10, s44, 5
	s_lshl_b32 s11, s20, 6
	s_and_b32 s45, s10, 0x60
	s_bitcmp0_b32 s21, 2
	s_cselect_b32 s21, s39, s43
	s_cselect_b32 s42, s38, s42
	s_lshl_b64 s[38:39], s[24:25], 2
	s_add_u32 s38, s42, s38
	s_addc_u32 s39, s21, s39
	s_lshl_b32 s21, s44, 4
	s_and_b32 s21, s21, 0xf80
	s_or_b32 s21, s21, s45
	v_or_b32_e32 v0, s21, v3
	v_or_b32_e32 v8, s11, v2
	v_lshlrev_b32_e32 v0, 2, v0
	v_lshl_add_u64 v[6:7], s[38:39], 0, v[0:1]
	v_mul_u32_u24_e32 v0, 0x2c00, v8
	v_lshl_add_u64 v[6:7], v[6:7], 0, v[0:1]
	s_movk_i32 s21, 0x5000
	v_add_co_u32_e32 v8, vcc, s21, v6
	s_mov_b32 s21, 0xb000
	s_nop 0
	v_addc_co_u32_e32 v9, vcc, 0, v7, vcc
	v_add_co_u32_e32 v50, vcc, s21, v6
	s_mov_b32 s21, 0x16000
	s_nop 0
	v_addc_co_u32_e32 v51, vcc, 0, v7, vcc
	v_add_co_u32_e32 v52, vcc, s48, v6
	s_lshl_b32 s20, s20, 8
	s_nop 0
	v_addc_co_u32_e32 v53, vcc, 0, v7, vcc
	v_add_co_u32_e32 v54, vcc, s21, v6
	s_mov_b32 s21, 0x1b000
	s_nop 0
	v_addc_co_u32_e32 v55, vcc, 0, v7, vcc
	v_add_co_u32_e32 v56, vcc, s21, v6
	s_mov_b32 s21, 0x21000
	s_nop 0
	v_addc_co_u32_e32 v57, vcc, 0, v7, vcc
	v_add_co_u32_e32 v58, vcc, s21, v6
	s_mov_b32 s21, 0x26000
	s_nop 0
	v_addc_co_u32_e32 v59, vcc, 0, v7, vcc
	v_add_co_u32_e32 v60, vcc, s21, v6
	s_mov_b32 s21, 0x2c000
	s_nop 0
	v_addc_co_u32_e32 v61, vcc, 0, v7, vcc
	global_load_dword v78, v[6:7], off
	global_load_dword v77, v[8:9], off offset:2048
	global_load_dword v76, v[50:51], off
	global_load_dword v75, v[52:53], off offset:2048
	global_load_dword v74, v[54:55], off
	global_load_dword v72, v[56:57], off offset:2048
	global_load_dword v70, v[58:59], off
	global_load_dword v68, v[60:61], off offset:2048
	v_add_co_u32_e32 v8, vcc, s21, v6
	s_mov_b32 s21, 0x31000
	s_nop 0
	v_addc_co_u32_e32 v9, vcc, 0, v7, vcc
	v_add_co_u32_e32 v50, vcc, s21, v6
	s_mov_b32 s21, 0x37000
	s_nop 0
	v_addc_co_u32_e32 v51, vcc, 0, v7, vcc
	v_add_co_u32_e32 v52, vcc, s21, v6
	s_mov_b32 s21, 0x3c000
	s_nop 0
	v_addc_co_u32_e32 v53, vcc, 0, v7, vcc
	v_add_co_u32_e32 v54, vcc, s21, v6
	s_mov_b32 s21, 0x42000
	s_nop 0
	v_addc_co_u32_e32 v55, vcc, 0, v7, vcc
	v_add_co_u32_e32 v56, vcc, s21, v6
	s_mov_b32 s21, 0x47000
	s_nop 0
	v_addc_co_u32_e32 v57, vcc, 0, v7, vcc
	v_add_co_u32_e32 v58, vcc, s21, v6
	s_mov_b32 s21, 0x4d000
	s_nop 0
	v_addc_co_u32_e32 v59, vcc, 0, v7, vcc
	v_add_co_u32_e32 v60, vcc, s21, v6
	s_mov_b32 s21, 0x52000
	s_nop 0
	v_addc_co_u32_e32 v61, vcc, 0, v7, vcc
	v_add_co_u32_e32 v80, vcc, s21, v6
	s_mov_b32 s21, 0x58000
	s_nop 0
	v_addc_co_u32_e32 v81, vcc, 0, v7, vcc
	global_load_dword v73, v[8:9], off
	global_load_dword v71, v[50:51], off offset:2048
	global_load_dword v69, v[52:53], off
	global_load_dword v67, v[54:55], off offset:2048
	global_load_dword v66, v[56:57], off
	global_load_dword v64, v[58:59], off offset:2048
	global_load_dword v62, v[60:61], off
	s_nop 0
	global_load_dword v60, v[80:81], off offset:2048
	v_add_co_u32_e32 v8, vcc, s21, v6
	s_mov_b32 s21, 0x5d000
	s_nop 0
	v_addc_co_u32_e32 v9, vcc, 0, v7, vcc
	v_add_co_u32_e32 v50, vcc, s21, v6
	s_mov_b32 s21, 0x63000
	s_nop 0
	v_addc_co_u32_e32 v51, vcc, 0, v7, vcc
	v_add_co_u32_e32 v52, vcc, s21, v6
	s_mov_b32 s21, 0x68000
	s_nop 0
	v_addc_co_u32_e32 v53, vcc, 0, v7, vcc
	v_add_co_u32_e32 v54, vcc, s21, v6
	s_mov_b32 s21, 0x6e000
	s_nop 0
	v_addc_co_u32_e32 v55, vcc, 0, v7, vcc
	v_add_co_u32_e32 v56, vcc, s21, v6
	s_mov_b32 s21, 0x73000
	s_nop 0
	v_addc_co_u32_e32 v57, vcc, 0, v7, vcc
	v_add_co_u32_e32 v80, vcc, s21, v6
	s_mov_b32 s21, 0x79000
	s_nop 0
	v_addc_co_u32_e32 v81, vcc, 0, v7, vcc
	v_add_co_u32_e32 v82, vcc, s21, v6
	s_mov_b32 s21, 0x7e000
	s_nop 0
	v_addc_co_u32_e32 v83, vcc, 0, v7, vcc
	v_add_co_u32_e32 v84, vcc, s21, v6
	s_mov_b32 s21, 0x84000
	s_nop 0
	v_addc_co_u32_e32 v85, vcc, 0, v7, vcc
	global_load_dword v65, v[8:9], off
	global_load_dword v63, v[50:51], off offset:2048
	global_load_dword v61, v[52:53], off
	global_load_dword v59, v[54:55], off offset:2048
	s_nop 0
	global_load_dword v57, v[56:57], off
	s_nop 0
	global_load_dword v55, v[80:81], off offset:2048
	global_load_dword v53, v[82:83], off
	global_load_dword v52, v[84:85], off offset:2048
	v_add_co_u32_e32 v8, vcc, s21, v6
	s_mov_b32 s21, 0x89000
	s_nop 0
	v_addc_co_u32_e32 v9, vcc, 0, v7, vcc
	v_add_co_u32_e32 v50, vcc, s21, v6
	s_mov_b32 s21, 0x8f000
	s_nop 0
	v_addc_co_u32_e32 v51, vcc, 0, v7, vcc
	v_add_co_u32_e32 v80, vcc, s21, v6
	s_mov_b32 s21, 0x94000
	s_nop 0
	v_addc_co_u32_e32 v81, vcc, 0, v7, vcc
	v_add_co_u32_e32 v82, vcc, s21, v6
	s_mov_b32 s21, 0x9a000
	s_nop 0
	v_addc_co_u32_e32 v83, vcc, 0, v7, vcc
	v_add_co_u32_e32 v84, vcc, s21, v6
	s_mov_b32 s21, 0x9f000
	s_nop 0
	v_addc_co_u32_e32 v85, vcc, 0, v7, vcc
	v_add_co_u32_e32 v86, vcc, s21, v6
	s_mov_b32 s21, 0xa5000
	s_nop 0
	v_addc_co_u32_e32 v87, vcc, 0, v7, vcc
	v_add_co_u32_e32 v88, vcc, s21, v6
	s_mov_b32 s21, 0xaa000
	s_nop 0
	v_addc_co_u32_e32 v89, vcc, 0, v7, vcc
	v_add_co_u32_e32 v6, vcc, s21, v6
	s_add_u32 s20, s6, s20
	s_nop 0
	v_addc_co_u32_e32 v7, vcc, 0, v7, vcc
	global_load_dword v58, v[8:9], off
	global_load_dword v56, v[50:51], off offset:2048
	global_load_dword v54, v[80:81], off
	s_nop 0
	global_load_dword v51, v[82:83], off offset:2048
	global_load_dword v50, v[84:85], off
	global_load_dword v49, v[86:87], off offset:2048
	global_load_dword v9, v[88:89], off
	global_load_dword v8, v[6:7], off offset:2048
	s_addc_u32 s21, s7, 0
	v_lshlrev_b32_e32 v0, 2, v2
	s_cmp_lg_u64 s[2:3], 0
	s_cselect_b64 s[6:7], -1, 0
	s_cmp_eq_u64 s[2:3], 0
	v_lshl_add_u64 v[6:7], s[20:21], 0, v[0:1]
	s_cbranch_scc1 .LBB0_583
	s_waitcnt vmcnt(31)
	global_load_dword v96, v[6:7], off offset:0
	global_load_dword v97, v[6:7], off offset:8
	global_load_dword v98, v[6:7], off offset:16
	global_load_dword v99, v[6:7], off offset:24
	global_load_dword v100, v[6:7], off offset:32
	global_load_dword v101, v[6:7], off offset:40
	global_load_dword v102, v[6:7], off offset:48
	global_load_dword v103, v[6:7], off offset:56
	global_load_dword v104, v[6:7], off offset:64
	global_load_dword v105, v[6:7], off offset:72
	global_load_dword v106, v[6:7], off offset:80
	global_load_dword v107, v[6:7], off offset:88
	global_load_dword v108, v[6:7], off offset:96
	global_load_dword v109, v[6:7], off offset:104
	global_load_dword v110, v[6:7], off offset:112
	global_load_dword v111, v[6:7], off offset:120
	global_load_dword v112, v[6:7], off offset:128
	global_load_dword v113, v[6:7], off offset:136
	global_load_dword v114, v[6:7], off offset:144
	global_load_dword v115, v[6:7], off offset:152
	global_load_dword v116, v[6:7], off offset:160
	global_load_dword v117, v[6:7], off offset:168
	global_load_dword v118, v[6:7], off offset:176
	global_load_dword v119, v[6:7], off offset:184
	global_load_dword v120, v[6:7], off offset:192
	global_load_dword v121, v[6:7], off offset:200
	global_load_dword v122, v[6:7], off offset:208
	global_load_dword v123, v[6:7], off offset:216
	global_load_dword v124, v[6:7], off offset:224
	global_load_dword v125, v[6:7], off offset:232
	global_load_dword v126, v[6:7], off offset:240
	global_load_dword v127, v[6:7], off offset:248
	s_branch .LBB0_584

.LBB0_738:
	s_or_b64 exec, exec, s[2:3]
	s_lshl_b32 s2, s4, 10
	s_ashr_i32 s3, s2, 31
	s_lshl_b64 s[2:3], s[2:3], 2
	s_add_u32 s2, s20, s2
	s_addc_u32 s3, s21, s3
	s_lshl_b32 s7, s6, 2
	s_add_u32 s10, s2, s7
	s_addc_u32 s11, s3, 0
	v_lshlrev_b32_e32 v0, 2, v2
	s_cmp_lg_u64 s[20:21], 0
	s_cselect_b64 s[2:3], -1, 0
	s_cmp_eq_u64 s[20:21], 0
	v_lshl_add_u64 v[6:7], s[10:11], 0, v[0:1]
	s_cbranch_scc1 .LBB0_740
	s_waitcnt vmcnt(31)
	global_load_dword v96, v[6:7], off offset:0
	global_load_dword v97, v[6:7], off offset:8
	global_load_dword v98, v[6:7], off offset:16
	global_load_dword v99, v[6:7], off offset:24
	global_load_dword v100, v[6:7], off offset:32
	global_load_dword v101, v[6:7], off offset:40
	global_load_dword v102, v[6:7], off offset:48
	global_load_dword v103, v[6:7], off offset:56
	global_load_dword v104, v[6:7], off offset:64
	global_load_dword v105, v[6:7], off offset:72
	global_load_dword v106, v[6:7], off offset:80
	global_load_dword v107, v[6:7], off offset:88
	global_load_dword v108, v[6:7], off offset:96
	global_load_dword v109, v[6:7], off offset:104
	global_load_dword v110, v[6:7], off offset:112
	global_load_dword v111, v[6:7], off offset:120
	global_load_dword v112, v[6:7], off offset:128
	global_load_dword v113, v[6:7], off offset:136
	global_load_dword v114, v[6:7], off offset:144
	global_load_dword v115, v[6:7], off offset:152
	global_load_dword v116, v[6:7], off offset:160
	global_load_dword v117, v[6:7], off offset:168
	global_load_dword v118, v[6:7], off offset:176
	global_load_dword v119, v[6:7], off offset:184
	global_load_dword v120, v[6:7], off offset:192
	global_load_dword v121, v[6:7], off offset:200
	global_load_dword v122, v[6:7], off offset:208
	global_load_dword v123, v[6:7], off offset:216
	global_load_dword v124, v[6:7], off offset:224
	global_load_dword v125, v[6:7], off offset:232
	global_load_dword v126, v[6:7], off offset:240
	global_load_dword v127, v[6:7], off offset:248
	s_branch .LBB0_741

.LBB0_873:
	s_lshl_b32 s2, s4, 10
	s_ashr_i32 s3, s2, 31
	s_lshl_b64 s[2:3], s[2:3], 2
	s_waitcnt lgkmcnt(0)
	s_add_u32 s4, s24, s2
	s_addc_u32 s7, s25, s3
	s_ashr_i32 s21, s20, 31
	s_lshl_b64 s[2:3], s[20:21], 2
	s_add_u32 s6, s4, s2
	s_addc_u32 s7, s7, s3
	v_lshlrev_b32_e32 v0, 2, v2
	s_cmp_lg_u64 s[24:25], 0
	s_cselect_b64 s[2:3], -1, 0
	s_cmp_eq_u64 s[24:25], 0
	v_lshl_add_u64 v[6:7], s[6:7], 0, v[0:1]
	s_cbranch_scc1 .LBB0_875
	s_waitcnt vmcnt(31)
	global_load_dword v96, v[6:7], off offset:0
	global_load_dword v97, v[6:7], off offset:8
	global_load_dword v98, v[6:7], off offset:16
	global_load_dword v99, v[6:7], off offset:24
	global_load_dword v100, v[6:7], off offset:32
	global_load_dword v101, v[6:7], off offset:40
	global_load_dword v102, v[6:7], off offset:48
	global_load_dword v103, v[6:7], off offset:56
	global_load_dword v104, v[6:7], off offset:64
	global_load_dword v105, v[6:7], off offset:72
	global_load_dword v106, v[6:7], off offset:80
	global_load_dword v107, v[6:7], off offset:88
	global_load_dword v108, v[6:7], off offset:96
	global_load_dword v109, v[6:7], off offset:104
	global_load_dword v110, v[6:7], off offset:112
	global_load_dword v111, v[6:7], off offset:120
	global_load_dword v112, v[6:7], off offset:128
	global_load_dword v113, v[6:7], off offset:136
	global_load_dword v114, v[6:7], off offset:144
	global_load_dword v115, v[6:7], off offset:152
	global_load_dword v116, v[6:7], off offset:160
	global_load_dword v117, v[6:7], off offset:168
	global_load_dword v118, v[6:7], off offset:176
	global_load_dword v119, v[6:7], off offset:184
	global_load_dword v120, v[6:7], off offset:192
	global_load_dword v121, v[6:7], off offset:200
	global_load_dword v122, v[6:7], off offset:208
	global_load_dword v123, v[6:7], off offset:216
	global_load_dword v124, v[6:7], off offset:224
	global_load_dword v125, v[6:7], off offset:232
	global_load_dword v126, v[6:7], off offset:240
	global_load_dword v127, v[6:7], off offset:248
	s_branch .LBB0_876
